# speedup vs baseline: 1.0030x; 1.0030x over previous
; #define tidx() tidx_(wv)
; __device__ __forceinline__ void transpose_tile(const float* __restrict__ W, bf16* __restrict__ Wt, int K, int N,
;                                                int k0, int n0, float* tile, int wv) {
;   const int tid = tidx();
;   const int r = tid >> 6, c4 = tid & 63;
;   const int n = n0 + c4 * 4;
;   float4 v[8];
; #pragma unroll
;   for (int i = 0; i < 8; ++i) {
;     if (n < N) v[i] = *(const float4*)(W + (long)(k0 + r + 8 * i) * N + n);
; __device__ __forceinline__ void transpose_phase(KP p, float* lds, int bid, int nb, int wv) {
;     ...
;   for (int j = bid; j < tot; j += nb) {
;     if (j < t1) {
;       int kt = j / 57, nt = j % 57;
;       transpose_tile(p->w_in, p->Wt1, D, PW, kt * 64, nt * 256, lds, wv);
.LBB0_23:
	s_and_b32 s20, s19, 63
	v_mbcnt_lo_u32_b32 v34, -1, 0
	v_mbcnt_hi_u32_b32 v34, -1, v34
	s_lshl_b32 s6, s20, 6
	v_lshlrev_b32_e32 v2, 2, v34
	v_and_b32_e32 v40, 0xfc, v2
	s_lshr_b32 s7, s19, 6
	s_lshl_b32 s7, s7, 8
	s_sub_i32 s20, s12, s7
	v_readlane_b32 s7, v253, 3
	v_subrev_u32_e32 v2, s20, v40
	v_add_u32_e32 v2, s12, v2
	v_or_b32_e32 v38, s7, v34
	v_ashrrev_i32_e32 v39, 6, v38
	v_ashrrev_i32_e32 v3, 31, v2
	v_cmp_gt_i32_e32 vcc, s14, v2
	v_add_u32_e32 v41, s6, v39
	v_lshl_add_u64 v[36:37], v[2:3], 2, s[2:3]
	v_mov_b32_e32 v2, 0
	v_mov_b32_e32 v3, 0
	v_mov_b32_e32 v4, 0
	v_mov_b32_e32 v5, 0
	s_and_saveexec_b64 s[10:11], vcc
	s_cbranch_execz .LBB0_25
	v_mad_i64_i32 v[2:3], s[22:23], v41, s15, v[36:37]
	global_load_dwordx4 v[2:5], v[2:3], off nt
